# P1 mix GEMM k-loops: mix-vector loads issued half an iteration ahead into spare VGPRs, counted vmcnt(8) instead of vmcnt(0)
# speedup vs baseline: 1.0488x; 1.0001x over previous
.LBB0_266:
	s_or_b64 exec, exec, s[28:29]
	s_and_b32 s3, s37, 0xffffff80
	v_or_b32_e32 v2, s3, v223
	v_ashrrev_i32_e32 v3, 31, v2
	v_lshlrev_b64 v[2:3], 11, v[2:3]
	v_lshl_add_u64 v[200:201], s[82:83], 0, v[2:3]
	v_or_b32_e32 v2, s3, v224
	v_ashrrev_i32_e32 v3, 31, v2
	v_lshlrev_b64 v[2:3], 11, v[2:3]
	v_lshl_add_u64 v[202:203], s[82:83], 0, v[2:3]
	v_or_b32_e32 v2, s3, v225
	v_ashrrev_i32_e32 v3, 31, v2
	v_lshlrev_b64 v[2:3], 11, v[2:3]
	v_lshl_add_u64 v[204:205], s[82:83], 0, v[2:3]
	v_or_b32_e32 v2, s3, v1
	s_mov_b32 s3, s21
	v_ashrrev_i32_e32 v3, 31, v2
	v_lshl_add_u64 v[208:209], v[186:187], 0, s[2:3]
	global_load_dwordx4 v[246:249], v[208:209], off
	global_load_dwordx4 v[250:253], v[208:209], off offset:-16
	s_add_u32 s2, s82, s20
	v_lshlrev_b64 v[2:3], 11, v[2:3]
	v_mov_b32_e32 v65, v172
	s_addc_u32 s3, s83, 0
	v_mov_b32_e32 v63, v172
	v_mov_b32_e32 v61, v172
	v_mov_b32_e32 v59, v172
	v_lshl_add_u64 v[206:207], s[82:83], 0, v[2:3]
	v_lshl_add_u64 v[210:211], s[2:3], 0, v[64:65]
	v_lshl_add_u64 v[212:213], s[2:3], 0, v[62:63]
	v_lshl_add_u64 v[214:215], s[2:3], 0, v[60:61]
	v_lshl_add_u64 v[216:217], s[2:3], 0, v[58:59]
	s_mov_b32 s20, 0
	v_mov_b32_e32 v51, v50
	v_mov_b32_e32 v52, v50
	v_mov_b32_e32 v53, v50
	v_mov_b32_e32 v54, v50
	v_mov_b32_e32 v55, v50
	v_mov_b32_e32 v56, v50
	v_mov_b32_e32 v57, v50
	v_mov_b32_e32 v58, v50
	v_mov_b32_e32 v59, v50
	v_mov_b32_e32 v60, v50
	v_mov_b32_e32 v61, v50
	v_mov_b32_e32 v62, v50
	v_mov_b32_e32 v63, v50
	v_mov_b32_e32 v64, v50
	v_mov_b32_e32 v65, v50
	v_mov_b32_e32 v34, v50
	v_mov_b32_e32 v35, v50
	v_mov_b32_e32 v36, v50
	v_mov_b32_e32 v37, v50
	v_mov_b32_e32 v38, v50
	v_mov_b32_e32 v39, v50
	v_mov_b32_e32 v40, v50
	v_mov_b32_e32 v41, v50
	v_mov_b32_e32 v42, v50
	v_mov_b32_e32 v43, v50
	v_mov_b32_e32 v44, v50
	v_mov_b32_e32 v45, v50
	v_mov_b32_e32 v46, v50
	v_mov_b32_e32 v47, v50
	v_mov_b32_e32 v48, v50
	v_mov_b32_e32 v49, v50
	v_mov_b32_e32 v18, v50
	v_mov_b32_e32 v19, v50
	v_mov_b32_e32 v20, v50
	v_mov_b32_e32 v21, v50
	v_mov_b32_e32 v22, v50
	v_mov_b32_e32 v23, v50
	v_mov_b32_e32 v24, v50
	v_mov_b32_e32 v25, v50
	v_mov_b32_e32 v26, v50
	v_mov_b32_e32 v27, v50
	v_mov_b32_e32 v28, v50
	v_mov_b32_e32 v29, v50
	v_mov_b32_e32 v30, v50
	v_mov_b32_e32 v31, v50
	v_mov_b32_e32 v32, v50
	v_mov_b32_e32 v33, v50
	v_mov_b32_e32 v2, v50
	v_mov_b32_e32 v3, v50
	v_mov_b32_e32 v4, v50
	v_mov_b32_e32 v5, v50
	v_mov_b32_e32 v6, v50
	v_mov_b32_e32 v7, v50
	v_mov_b32_e32 v8, v50
	v_mov_b32_e32 v9, v50
	v_mov_b32_e32 v10, v50
	v_mov_b32_e32 v11, v50
	v_mov_b32_e32 v12, v50
	v_mov_b32_e32 v13, v50
	v_mov_b32_e32 v14, v50
	v_mov_b32_e32 v15, v50
	v_mov_b32_e32 v16, v50
	v_mov_b32_e32 v17, v50
	s_waitcnt lgkmcnt(0)
	s_barrier
	s_waitcnt vmcnt(0)
	s_branch .LBB0_269

.LBB0_269:
	s_waitcnt vmcnt(8)
	v_lshlrev_b32_e32 v230, 16, v66
	v_and_b32_e32 v231, 0xffff0000, v66
	v_lshlrev_b32_e32 v232, 16, v70
	v_and_b32_e32 v233, 0xffff0000, v70
	v_pk_add_f32 v[232:233], v[232:233], v[230:231] neg_lo:[0,1] neg_hi:[0,1]
	v_lshlrev_b32_e32 v234, 16, v71
	v_and_b32_e32 v235, 0xffff0000, v71
	v_lshlrev_b32_e32 v236, 16, v73
	v_and_b32_e32 v237, 0xffff0000, v73
	s_cmp_gt_u32 s20, 12
	v_pk_fma_f32 v[230:231], v[232:233], v[250:251], v[230:231]
	v_lshlrev_b32_e32 v232, 16, v67
	v_and_b32_e32 v233, 0xffff0000, v67
	v_pk_add_f32 v[234:235], v[234:235], v[232:233] neg_lo:[0,1] neg_hi:[0,1]
	v_cvt_pk_bf16_f32 v230, v230, v231
	v_pk_fma_f32 v[232:233], v[234:235], v[252:253], v[232:233]
	v_lshlrev_b32_e32 v234, 16, v72
	v_cvt_pk_bf16_f32 v231, v232, v233
	v_lshlrev_b32_e32 v232, 16, v68
	v_and_b32_e32 v233, 0xffff0000, v68
	v_and_b32_e32 v235, 0xffff0000, v72
	v_pk_add_f32 v[234:235], v[234:235], v[232:233] neg_lo:[0,1] neg_hi:[0,1]
	s_nop 0
	v_pk_fma_f32 v[232:233], v[234:235], v[246:247], v[232:233]
	v_lshlrev_b32_e32 v234, 16, v69
	v_and_b32_e32 v235, 0xffff0000, v69
	v_pk_add_f32 v[236:237], v[236:237], v[234:235] neg_lo:[0,1] neg_hi:[0,1]
	v_cvt_pk_bf16_f32 v232, v232, v233
	v_pk_fma_f32 v[234:235], v[236:237], v[248:249], v[234:235]
	v_lshlrev_b32_e32 v236, 16, v89
	v_cvt_pk_bf16_f32 v233, v234, v235
	ds_write_b128 v219, v[230:233] offset:36864
	ds_write_b128 v219, v[74:77] offset:55296
	v_lshlrev_b32_e32 v230, 16, v82
	v_and_b32_e32 v231, 0xffff0000, v82
	v_lshlrev_b32_e32 v232, 16, v86
	v_and_b32_e32 v233, 0xffff0000, v86
	v_pk_add_f32 v[232:233], v[232:233], v[230:231] neg_lo:[0,1] neg_hi:[0,1]
	v_lshlrev_b32_e32 v234, 16, v87
	v_pk_fma_f32 v[230:231], v[232:233], v[250:251], v[230:231]
	v_lshlrev_b32_e32 v232, 16, v83
	v_and_b32_e32 v233, 0xffff0000, v83
	v_and_b32_e32 v235, 0xffff0000, v87
	v_pk_add_f32 v[234:235], v[234:235], v[232:233] neg_lo:[0,1] neg_hi:[0,1]
	v_cvt_pk_bf16_f32 v230, v230, v231
	v_pk_fma_f32 v[232:233], v[234:235], v[252:253], v[232:233]
	v_lshlrev_b32_e32 v234, 16, v88
	v_cvt_pk_bf16_f32 v231, v232, v233
	v_lshlrev_b32_e32 v232, 16, v84
	v_and_b32_e32 v233, 0xffff0000, v84
	v_and_b32_e32 v235, 0xffff0000, v88
	v_pk_add_f32 v[234:235], v[234:235], v[232:233] neg_lo:[0,1] neg_hi:[0,1]
	v_and_b32_e32 v237, 0xffff0000, v89
	v_pk_fma_f32 v[232:233], v[234:235], v[246:247], v[232:233]
	v_lshlrev_b32_e32 v234, 16, v85
	v_and_b32_e32 v235, 0xffff0000, v85
	v_pk_add_f32 v[236:237], v[236:237], v[234:235] neg_lo:[0,1] neg_hi:[0,1]
	v_cvt_pk_bf16_f32 v232, v232, v233
	v_pk_fma_f32 v[234:235], v[236:237], v[248:249], v[234:235]
	v_lshlrev_b32_e32 v236, 16, v97
	v_cvt_pk_bf16_f32 v233, v234, v235
	ds_write_b128 v219, v[230:233] offset:41472
	ds_write_b128 v219, v[78:81] offset:59904
	v_lshlrev_b32_e32 v230, 16, v90
	v_and_b32_e32 v231, 0xffff0000, v90
	v_lshlrev_b32_e32 v232, 16, v94
	v_and_b32_e32 v233, 0xffff0000, v94
	v_pk_add_f32 v[232:233], v[232:233], v[230:231] neg_lo:[0,1] neg_hi:[0,1]
	v_lshlrev_b32_e32 v234, 16, v95
	v_pk_fma_f32 v[230:231], v[232:233], v[250:251], v[230:231]
	v_lshlrev_b32_e32 v232, 16, v91
	v_and_b32_e32 v233, 0xffff0000, v91
	v_and_b32_e32 v235, 0xffff0000, v95
	v_pk_add_f32 v[234:235], v[234:235], v[232:233] neg_lo:[0,1] neg_hi:[0,1]
	v_cvt_pk_bf16_f32 v230, v230, v231
	v_pk_fma_f32 v[232:233], v[234:235], v[252:253], v[232:233]
	v_lshlrev_b32_e32 v234, 16, v96
	v_cvt_pk_bf16_f32 v231, v232, v233
	v_lshlrev_b32_e32 v232, 16, v92
	v_and_b32_e32 v233, 0xffff0000, v92
	v_and_b32_e32 v235, 0xffff0000, v96
	v_pk_add_f32 v[234:235], v[234:235], v[232:233] neg_lo:[0,1] neg_hi:[0,1]
	v_and_b32_e32 v237, 0xffff0000, v97
	v_pk_fma_f32 v[232:233], v[234:235], v[246:247], v[232:233]
	v_lshlrev_b32_e32 v234, 16, v93
	v_and_b32_e32 v235, 0xffff0000, v93
	v_pk_add_f32 v[236:237], v[236:237], v[234:235] neg_lo:[0,1] neg_hi:[0,1]
	v_cvt_pk_bf16_f32 v232, v232, v233
	v_pk_fma_f32 v[234:235], v[236:237], v[248:249], v[234:235]
	s_nop 0
	v_cvt_pk_bf16_f32 v233, v234, v235
	ds_write_b128 v219, v[230:233] offset:46080
	ds_write_b128 v219, v[98:101] offset:64512
	v_lshlrev_b32_e32 v230, 16, v102
	v_and_b32_e32 v231, 0xffff0000, v102
	v_lshlrev_b32_e32 v232, 16, v106
	v_and_b32_e32 v233, 0xffff0000, v106
	v_pk_add_f32 v[232:233], v[232:233], v[230:231] neg_lo:[0,1] neg_hi:[0,1]
	s_nop 0
	v_pk_fma_f32 v[166:167], v[232:233], v[250:251], v[230:231]
	v_lshlrev_b32_e32 v230, 16, v103
	v_and_b32_e32 v231, 0xffff0000, v103
	v_lshlrev_b32_e32 v232, 16, v107
	v_and_b32_e32 v233, 0xffff0000, v107
	v_pk_add_f32 v[232:233], v[232:233], v[230:231] neg_lo:[0,1] neg_hi:[0,1]
	v_cvt_pk_bf16_f32 v166, v166, v167
	v_pk_fma_f32 v[168:169], v[232:233], v[252:253], v[230:231]
	v_lshlrev_b32_e32 v230, 16, v108
	v_cvt_pk_bf16_f32 v167, v168, v169
	v_lshlrev_b32_e32 v168, 16, v104
	v_and_b32_e32 v169, 0xffff0000, v104
	v_and_b32_e32 v231, 0xffff0000, v108
	v_pk_add_f32 v[230:231], v[230:231], v[168:169] neg_lo:[0,1] neg_hi:[0,1]
	s_nop 0
	v_pk_fma_f32 v[162:163], v[230:231], v[246:247], v[168:169]
	v_lshlrev_b32_e32 v230, 16, v109
	v_cvt_pk_bf16_f32 v168, v162, v163
	v_lshlrev_b32_e32 v162, 16, v105
	v_and_b32_e32 v163, 0xffff0000, v105
	v_and_b32_e32 v231, 0xffff0000, v109
	v_pk_add_f32 v[230:231], v[230:231], v[162:163] neg_lo:[0,1] neg_hi:[0,1]
	s_nop 0
	v_pk_fma_f32 v[162:163], v[230:231], v[248:249], v[162:163]
	s_nop 0
	v_cvt_pk_bf16_f32 v169, v162, v163
	ds_write_b128 v219, v[166:169] offset:50688
	ds_write_b128 v221, v[110:113] offset:13824
	s_cbranch_scc1 .LBB0_279
	global_load_dwordx4 v[246:249], v[208:209], off offset:256
	global_load_dwordx4 v[250:253], v[208:209], off offset:240
	v_lshl_add_u64 v[66:67], v[206:207], 0, v[188:189]
	v_add_co_u32_e32 v66, vcc, 0xa380000, v66
	v_lshl_add_u64 v[70:71], v[192:193], 0, v[188:189]
	s_nop 0
	v_addc_co_u32_e32 v67, vcc, 0, v67, vcc
	global_load_dwordx4 v[66:69], v[66:67], off offset:384
	v_mov_b32_e32 v80, 0
	global_load_dwordx4 v[70:73], v[70:71], off offset:384
	v_mov_b32_e32 v81, v172
	v_mov_b64_e32 v[76:77], v[80:81]
	v_mov_b64_e32 v[74:75], v[80:81]
	s_and_saveexec_b64 s[2:3], s[4:5]
	s_cbranch_execz .LBB0_272
	v_lshl_add_u64 v[74:75], v[216:217], 0, v[188:189]
	global_load_dwordx4 v[74:77], v[74:75], off offset:384

.LBB0_279:
	ds_read_b128 v[162:165], v227
	ds_read_b128 v[166:169], v228 offset:18432
	ds_read_b128 v[230:233], v228 offset:23040
	s_cmp_gt_u32 s20, 13
	s_cselect_b64 s[2:3], -1, 0
	s_and_b64 vcc, exec, s[2:3]
	s_waitcnt lgkmcnt(1)
	v_mfma_f32_32x32x16_bf16 v[50:65], v[162:165], v[166:169], v[50:65]
	s_waitcnt lgkmcnt(0)
	v_mfma_f32_32x32x16_bf16 v[34:49], v[162:165], v[230:233], v[34:49]
	ds_read_b128 v[162:165], v227 offset:4608
	s_waitcnt lgkmcnt(0)
	v_mfma_f32_32x32x16_bf16 v[18:33], v[162:165], v[166:169], v[18:33]
	v_mfma_f32_32x32x16_bf16 v[2:17], v[162:165], v[230:233], v[2:17]
	ds_read_b128 v[162:165], v227 offset:32
	ds_read_b128 v[166:169], v228 offset:18464
	ds_read_b128 v[230:233], v228 offset:23072
	s_waitcnt lgkmcnt(1)
	v_mfma_f32_32x32x16_bf16 v[50:65], v[162:165], v[166:169], v[50:65]
	s_waitcnt lgkmcnt(0)
	v_mfma_f32_32x32x16_bf16 v[34:49], v[162:165], v[230:233], v[34:49]
	ds_read_b128 v[162:165], v227 offset:4640
	s_waitcnt lgkmcnt(0)
	v_mfma_f32_32x32x16_bf16 v[18:33], v[162:165], v[166:169], v[18:33]
	v_mfma_f32_32x32x16_bf16 v[2:17], v[162:165], v[230:233], v[2:17]
	ds_read_b128 v[162:165], v227 offset:64
	ds_read_b128 v[166:169], v228 offset:18496
	ds_read_b128 v[230:233], v228 offset:23104
	s_waitcnt lgkmcnt(1)
	v_mfma_f32_32x32x16_bf16 v[50:65], v[162:165], v[166:169], v[50:65]
	s_waitcnt lgkmcnt(0)
	v_mfma_f32_32x32x16_bf16 v[34:49], v[162:165], v[230:233], v[34:49]
	ds_read_b128 v[162:165], v227 offset:4672
	s_waitcnt lgkmcnt(0)
	v_mfma_f32_32x32x16_bf16 v[18:33], v[162:165], v[166:169], v[18:33]
	v_mfma_f32_32x32x16_bf16 v[2:17], v[162:165], v[230:233], v[2:17]
	ds_read_b128 v[162:165], v227 offset:96
	ds_read_b128 v[166:169], v228 offset:18528
	ds_read_b128 v[230:233], v228 offset:23136
	s_waitcnt lgkmcnt(1)
	v_mfma_f32_32x32x16_bf16 v[50:65], v[162:165], v[166:169], v[50:65]
	s_waitcnt lgkmcnt(0)
	v_mfma_f32_32x32x16_bf16 v[34:49], v[162:165], v[230:233], v[34:49]
	ds_read_b128 v[162:165], v227 offset:4704
	s_waitcnt lgkmcnt(0)
	s_barrier
	v_mfma_f32_32x32x16_bf16 v[18:33], v[162:165], v[166:169], v[18:33]
	v_mfma_f32_32x32x16_bf16 v[2:17], v[162:165], v[230:233], v[2:17]
	s_cbranch_vccnz .LBB0_268
	s_waitcnt vmcnt(8)
	v_lshlrev_b32_e32 v230, 16, v114
	v_and_b32_e32 v231, 0xffff0000, v114
	v_lshlrev_b32_e32 v232, 16, v118
	v_and_b32_e32 v233, 0xffff0000, v118
	v_pk_add_f32 v[232:233], v[232:233], v[230:231] neg_lo:[0,1] neg_hi:[0,1]
	v_lshlrev_b32_e32 v234, 16, v119
	v_and_b32_e32 v235, 0xffff0000, v119
	v_lshlrev_b32_e32 v236, 16, v121
	v_and_b32_e32 v237, 0xffff0000, v121
	s_cmp_gt_u32 s20, 11
	v_pk_fma_f32 v[230:231], v[232:233], v[250:251], v[230:231]
	v_lshlrev_b32_e32 v232, 16, v115
	v_and_b32_e32 v233, 0xffff0000, v115
	v_pk_add_f32 v[234:235], v[234:235], v[232:233] neg_lo:[0,1] neg_hi:[0,1]
	v_cvt_pk_bf16_f32 v230, v230, v231
	v_pk_fma_f32 v[232:233], v[234:235], v[252:253], v[232:233]
	v_lshlrev_b32_e32 v234, 16, v120
	v_cvt_pk_bf16_f32 v231, v232, v233
	v_lshlrev_b32_e32 v232, 16, v116
	v_and_b32_e32 v233, 0xffff0000, v116
	v_and_b32_e32 v235, 0xffff0000, v120
	v_pk_add_f32 v[234:235], v[234:235], v[232:233] neg_lo:[0,1] neg_hi:[0,1]
	s_nop 0
	v_pk_fma_f32 v[232:233], v[234:235], v[246:247], v[232:233]
	v_lshlrev_b32_e32 v234, 16, v117
	v_and_b32_e32 v235, 0xffff0000, v117
	v_pk_add_f32 v[236:237], v[236:237], v[234:235] neg_lo:[0,1] neg_hi:[0,1]
	v_cvt_pk_bf16_f32 v232, v232, v233
	v_pk_fma_f32 v[234:235], v[236:237], v[248:249], v[234:235]
	v_lshlrev_b32_e32 v236, 16, v137
	v_cvt_pk_bf16_f32 v233, v234, v235
	ds_write_b128 v219, v[230:233]
	ds_write_b128 v219, v[122:125] offset:18432
	v_lshlrev_b32_e32 v230, 16, v130
	v_and_b32_e32 v231, 0xffff0000, v130
	v_lshlrev_b32_e32 v232, 16, v134
	v_and_b32_e32 v233, 0xffff0000, v134
	v_pk_add_f32 v[232:233], v[232:233], v[230:231] neg_lo:[0,1] neg_hi:[0,1]
	v_lshlrev_b32_e32 v234, 16, v135
	v_pk_fma_f32 v[230:231], v[232:233], v[250:251], v[230:231]
	v_lshlrev_b32_e32 v232, 16, v131
	v_and_b32_e32 v233, 0xffff0000, v131
	v_and_b32_e32 v235, 0xffff0000, v135
	v_pk_add_f32 v[234:235], v[234:235], v[232:233] neg_lo:[0,1] neg_hi:[0,1]
	v_cvt_pk_bf16_f32 v230, v230, v231
	v_pk_fma_f32 v[232:233], v[234:235], v[252:253], v[232:233]
	v_lshlrev_b32_e32 v234, 16, v136
	v_cvt_pk_bf16_f32 v231, v232, v233
	v_lshlrev_b32_e32 v232, 16, v132
	v_and_b32_e32 v233, 0xffff0000, v132
	v_and_b32_e32 v235, 0xffff0000, v136
	v_pk_add_f32 v[234:235], v[234:235], v[232:233] neg_lo:[0,1] neg_hi:[0,1]
	v_and_b32_e32 v237, 0xffff0000, v137
	v_pk_fma_f32 v[232:233], v[234:235], v[246:247], v[232:233]
	v_lshlrev_b32_e32 v234, 16, v133
	v_and_b32_e32 v235, 0xffff0000, v133
	v_pk_add_f32 v[236:237], v[236:237], v[234:235] neg_lo:[0,1] neg_hi:[0,1]
	v_cvt_pk_bf16_f32 v232, v232, v233
	v_pk_fma_f32 v[234:235], v[236:237], v[248:249], v[234:235]
	v_lshlrev_b32_e32 v236, 16, v145
	v_cvt_pk_bf16_f32 v233, v234, v235
	ds_write_b128 v219, v[230:233] offset:4608
	ds_write_b128 v219, v[126:129] offset:23040
	v_lshlrev_b32_e32 v230, 16, v138
	v_and_b32_e32 v231, 0xffff0000, v138
	v_lshlrev_b32_e32 v232, 16, v142
	v_and_b32_e32 v233, 0xffff0000, v142
	v_pk_add_f32 v[232:233], v[232:233], v[230:231] neg_lo:[0,1] neg_hi:[0,1]
	v_lshlrev_b32_e32 v234, 16, v143
	v_pk_fma_f32 v[230:231], v[232:233], v[250:251], v[230:231]
	v_lshlrev_b32_e32 v232, 16, v139
	v_and_b32_e32 v233, 0xffff0000, v139
	v_and_b32_e32 v235, 0xffff0000, v143
	v_pk_add_f32 v[234:235], v[234:235], v[232:233] neg_lo:[0,1] neg_hi:[0,1]
	v_cvt_pk_bf16_f32 v230, v230, v231
	v_pk_fma_f32 v[232:233], v[234:235], v[252:253], v[232:233]
	v_lshlrev_b32_e32 v234, 16, v144
	v_cvt_pk_bf16_f32 v231, v232, v233
	v_lshlrev_b32_e32 v232, 16, v140
	v_and_b32_e32 v233, 0xffff0000, v140
	v_and_b32_e32 v235, 0xffff0000, v144
	v_pk_add_f32 v[234:235], v[234:235], v[232:233] neg_lo:[0,1] neg_hi:[0,1]
	v_and_b32_e32 v237, 0xffff0000, v145
	v_pk_fma_f32 v[232:233], v[234:235], v[246:247], v[232:233]
	v_lshlrev_b32_e32 v234, 16, v141
	v_and_b32_e32 v235, 0xffff0000, v141
	v_pk_add_f32 v[236:237], v[236:237], v[234:235] neg_lo:[0,1] neg_hi:[0,1]
	v_cvt_pk_bf16_f32 v232, v232, v233
	v_pk_fma_f32 v[234:235], v[236:237], v[248:249], v[234:235]
	s_nop 0
	v_cvt_pk_bf16_f32 v233, v234, v235
	ds_write_b128 v219, v[230:233] offset:9216
	ds_write_b128 v219, v[146:149] offset:27648
	v_lshlrev_b32_e32 v230, 16, v150
	v_and_b32_e32 v231, 0xffff0000, v150
	v_lshlrev_b32_e32 v232, 16, v154
	v_and_b32_e32 v233, 0xffff0000, v154
	v_pk_add_f32 v[232:233], v[232:233], v[230:231] neg_lo:[0,1] neg_hi:[0,1]
	s_nop 0
	v_pk_fma_f32 v[166:167], v[232:233], v[250:251], v[230:231]
	v_lshlrev_b32_e32 v230, 16, v151
	v_and_b32_e32 v231, 0xffff0000, v151
	v_lshlrev_b32_e32 v232, 16, v155
	v_and_b32_e32 v233, 0xffff0000, v155
	v_pk_add_f32 v[232:233], v[232:233], v[230:231] neg_lo:[0,1] neg_hi:[0,1]
	v_cvt_pk_bf16_f32 v166, v166, v167
	v_pk_fma_f32 v[168:169], v[232:233], v[252:253], v[230:231]
	v_lshlrev_b32_e32 v230, 16, v156
	v_cvt_pk_bf16_f32 v167, v168, v169
	v_lshlrev_b32_e32 v168, 16, v152
	v_and_b32_e32 v169, 0xffff0000, v152
	v_and_b32_e32 v231, 0xffff0000, v156
	v_pk_add_f32 v[230:231], v[230:231], v[168:169] neg_lo:[0,1] neg_hi:[0,1]
	s_nop 0
	v_pk_fma_f32 v[162:163], v[230:231], v[246:247], v[168:169]
	v_lshlrev_b32_e32 v230, 16, v157
	v_cvt_pk_bf16_f32 v168, v162, v163
	v_lshlrev_b32_e32 v162, 16, v153
	v_and_b32_e32 v163, 0xffff0000, v153
	v_and_b32_e32 v231, 0xffff0000, v157
	v_pk_add_f32 v[230:231], v[230:231], v[162:163] neg_lo:[0,1] neg_hi:[0,1]
	s_nop 0
	v_pk_fma_f32 v[162:163], v[230:231], v[248:249], v[162:163]
	s_nop 0
	v_cvt_pk_bf16_f32 v169, v162, v163
	ds_write_b128 v219, v[166:169] offset:13824
	ds_write_b128 v219, v[158:161] offset:32256
	global_load_dwordx4 v[246:249], v[208:209], off offset:512
	global_load_dwordx4 v[250:253], v[208:209], off offset:496
	s_cbranch_scc1 .Lmixpf_a_last
	v_lshl_add_u64 v[114:115], v[206:207], 0, v[188:189]
	v_add_co_u32_e32 v114, vcc, 0xa380000, v114
	v_lshl_add_u64 v[118:119], v[192:193], 0, v[188:189]
	s_nop 0
	v_addc_co_u32_e32 v115, vcc, 0, v115, vcc
	global_load_dwordx4 v[114:117], v[114:115], off offset:512
	v_mov_b32_e32 v128, 0
	global_load_dwordx4 v[118:121], v[118:119], off offset:512
	v_mov_b32_e32 v129, v172
	v_mov_b64_e32 v[124:125], v[128:129]
	v_mov_b64_e32 v[122:123], v[128:129]
	s_and_saveexec_b64 s[28:29], s[4:5]
	s_cbranch_execz .LBB0_283
	v_lshl_add_u64 v[122:123], v[216:217], 0, v[188:189]
	global_load_dwordx4 v[122:125], v[122:123], off offset:512

.Lmixpf_a_last:
	s_waitcnt vmcnt(0)
	s_branch .LBB0_268

.LBB0_672:
	s_or_b64 exec, exec, s[22:23]
	s_lshl_b32 s22, s28, 11
	s_and_b32 s22, s22, 0x1c0000
	s_add_u32 s2, s26, s2
	v_lshl_or_b32 v4, v171, 1, s22
	v_mov_b32_e32 v5, v172
	v_mov_b32_e32 v165, v172
	s_addc_u32 s3, s27, s3
	v_mov_b32_e32 v163, v172
	v_mov_b32_e32 v63, v172
	v_lshl_add_u64 v[194:195], v[178:179], 0, s[14:15]
	global_load_dwordx4 v[246:249], v[194:195], off
	global_load_dwordx4 v[250:253], v[194:195], off offset:-16
	v_lshl_add_u64 v[196:197], s[2:3], 0, v[164:165]
	v_lshl_add_u64 v[198:199], s[82:83], 0, v[166:167]
	v_lshl_add_u64 v[200:201], s[82:83], 0, v[60:61]
	v_lshl_add_u64 v[202:203], s[2:3], 0, v[162:163]
	v_lshl_add_u64 v[204:205], s[82:83], 0, v[64:65]
	v_lshl_add_u64 v[206:207], s[2:3], 0, v[62:63]
	v_lshl_add_u64 v[208:209], s[82:83], 0, v[58:59]
	v_lshl_add_u64 v[210:211], s[2:3], 0, v[4:5]
	s_mov_b32 s14, 0
	v_mov_b32_e32 v3, v2
	v_mov_b32_e32 v4, v2
	v_mov_b32_e32 v5, v2
	v_mov_b32_e32 v6, v2
	v_mov_b32_e32 v7, v2
	v_mov_b32_e32 v8, v2
	v_mov_b32_e32 v9, v2
	v_mov_b32_e32 v10, v2
	v_mov_b32_e32 v11, v2
	v_mov_b32_e32 v12, v2
	v_mov_b32_e32 v13, v2
	v_mov_b32_e32 v14, v2
	v_mov_b32_e32 v15, v2
	v_mov_b32_e32 v16, v2
	v_mov_b32_e32 v17, v2
	v_mov_b32_e32 v18, v2
	v_mov_b32_e32 v19, v2
	v_mov_b32_e32 v20, v2
	v_mov_b32_e32 v21, v2
	v_mov_b32_e32 v22, v2
	v_mov_b32_e32 v23, v2
	v_mov_b32_e32 v24, v2
	v_mov_b32_e32 v25, v2
	v_mov_b32_e32 v26, v2
	v_mov_b32_e32 v27, v2
	v_mov_b32_e32 v28, v2
	v_mov_b32_e32 v29, v2
	v_mov_b32_e32 v30, v2
	v_mov_b32_e32 v31, v2
	v_mov_b32_e32 v32, v2
	v_mov_b32_e32 v33, v2
	v_mov_b32_e32 v34, v2
	v_mov_b32_e32 v35, v2
	v_mov_b32_e32 v36, v2
	v_mov_b32_e32 v37, v2
	v_mov_b32_e32 v38, v2
	v_mov_b32_e32 v39, v2
	v_mov_b32_e32 v40, v2
	v_mov_b32_e32 v41, v2
	v_mov_b32_e32 v42, v2
	v_mov_b32_e32 v43, v2
	v_mov_b32_e32 v44, v2
	v_mov_b32_e32 v45, v2
	v_mov_b32_e32 v46, v2
	v_mov_b32_e32 v47, v2
	v_mov_b32_e32 v48, v2
	v_mov_b32_e32 v49, v2
	v_mov_b32_e32 v50, v2
	v_mov_b32_e32 v51, v2
	v_mov_b32_e32 v52, v2
	v_mov_b32_e32 v53, v2
	v_mov_b32_e32 v54, v2
	v_mov_b32_e32 v55, v2
	v_mov_b32_e32 v56, v2
	v_mov_b32_e32 v57, v2
	v_mov_b32_e32 v58, v2
	v_mov_b32_e32 v59, v2
	v_mov_b32_e32 v60, v2
	v_mov_b32_e32 v61, v2
	v_mov_b32_e32 v62, v2
	v_mov_b32_e32 v63, v2
	v_mov_b32_e32 v64, v2
	v_mov_b32_e32 v65, v2
	s_waitcnt lgkmcnt(0)
	s_barrier
	s_waitcnt vmcnt(0)
	s_branch .LBB0_675

.LBB0_675:
	s_waitcnt vmcnt(8)
	v_lshlrev_b32_e32 v234, 16, v66
	v_and_b32_e32 v235, 0xffff0000, v66
	v_lshlrev_b32_e32 v236, 16, v70
	v_and_b32_e32 v237, 0xffff0000, v70
	v_pk_add_f32 v[236:237], v[236:237], v[234:235] neg_lo:[0,1] neg_hi:[0,1]
	v_lshlrev_b32_e32 v238, 16, v71
	v_and_b32_e32 v239, 0xffff0000, v71
	v_lshlrev_b32_e32 v240, 16, v73
	v_and_b32_e32 v241, 0xffff0000, v73
	s_cmp_gt_u32 s14, 12
	v_pk_fma_f32 v[234:235], v[236:237], v[250:251], v[234:235]
	v_lshlrev_b32_e32 v236, 16, v67
	v_and_b32_e32 v237, 0xffff0000, v67
	v_pk_add_f32 v[238:239], v[238:239], v[236:237] neg_lo:[0,1] neg_hi:[0,1]
	v_cvt_pk_bf16_f32 v234, v234, v235
	v_pk_fma_f32 v[236:237], v[238:239], v[252:253], v[236:237]
	v_lshlrev_b32_e32 v238, 16, v72
	v_cvt_pk_bf16_f32 v235, v236, v237
	v_lshlrev_b32_e32 v236, 16, v68
	v_and_b32_e32 v237, 0xffff0000, v68
	v_and_b32_e32 v239, 0xffff0000, v72
	v_pk_add_f32 v[238:239], v[238:239], v[236:237] neg_lo:[0,1] neg_hi:[0,1]
	s_nop 0
	v_pk_fma_f32 v[236:237], v[238:239], v[246:247], v[236:237]
	v_lshlrev_b32_e32 v238, 16, v69
	v_and_b32_e32 v239, 0xffff0000, v69
	v_pk_add_f32 v[240:241], v[240:241], v[238:239] neg_lo:[0,1] neg_hi:[0,1]
	v_cvt_pk_bf16_f32 v236, v236, v237
	v_pk_fma_f32 v[238:239], v[240:241], v[248:249], v[238:239]
	v_lshlrev_b32_e32 v240, 16, v85
	v_cvt_pk_bf16_f32 v237, v238, v239
	ds_write_b128 v213, v[234:237] offset:36864
	ds_write_b128 v213, v[74:77] offset:55296
	v_lshlrev_b32_e32 v234, 16, v78
	v_and_b32_e32 v235, 0xffff0000, v78
	v_lshlrev_b32_e32 v236, 16, v82
	v_and_b32_e32 v237, 0xffff0000, v82
	v_pk_add_f32 v[236:237], v[236:237], v[234:235] neg_lo:[0,1] neg_hi:[0,1]
	v_lshlrev_b32_e32 v238, 16, v83
	v_pk_fma_f32 v[234:235], v[236:237], v[250:251], v[234:235]
	v_lshlrev_b32_e32 v236, 16, v79
	v_and_b32_e32 v237, 0xffff0000, v79
	v_and_b32_e32 v239, 0xffff0000, v83
	v_pk_add_f32 v[238:239], v[238:239], v[236:237] neg_lo:[0,1] neg_hi:[0,1]
	v_cvt_pk_bf16_f32 v234, v234, v235
	v_pk_fma_f32 v[236:237], v[238:239], v[252:253], v[236:237]
	v_lshlrev_b32_e32 v238, 16, v84
	v_cvt_pk_bf16_f32 v235, v236, v237
	v_lshlrev_b32_e32 v236, 16, v80
	v_and_b32_e32 v237, 0xffff0000, v80
	v_and_b32_e32 v239, 0xffff0000, v84
	v_pk_add_f32 v[238:239], v[238:239], v[236:237] neg_lo:[0,1] neg_hi:[0,1]
	v_and_b32_e32 v241, 0xffff0000, v85
	v_pk_fma_f32 v[236:237], v[238:239], v[246:247], v[236:237]
	v_lshlrev_b32_e32 v238, 16, v81
	v_and_b32_e32 v239, 0xffff0000, v81
	v_pk_add_f32 v[240:241], v[240:241], v[238:239] neg_lo:[0,1] neg_hi:[0,1]
	v_cvt_pk_bf16_f32 v236, v236, v237
	v_pk_fma_f32 v[238:239], v[240:241], v[248:249], v[238:239]
	v_lshlrev_b32_e32 v240, 16, v101
	v_cvt_pk_bf16_f32 v237, v238, v239
	ds_write_b128 v213, v[234:237] offset:41472
	ds_write_b128 v213, v[86:89] offset:59904
	v_lshlrev_b32_e32 v234, 16, v94
	v_and_b32_e32 v235, 0xffff0000, v94
	v_lshlrev_b32_e32 v236, 16, v98
	v_and_b32_e32 v237, 0xffff0000, v98
	v_pk_add_f32 v[236:237], v[236:237], v[234:235] neg_lo:[0,1] neg_hi:[0,1]
	v_lshlrev_b32_e32 v238, 16, v99
	v_pk_fma_f32 v[234:235], v[236:237], v[250:251], v[234:235]
	v_lshlrev_b32_e32 v236, 16, v95
	v_and_b32_e32 v237, 0xffff0000, v95
	v_and_b32_e32 v239, 0xffff0000, v99
	v_pk_add_f32 v[238:239], v[238:239], v[236:237] neg_lo:[0,1] neg_hi:[0,1]
	v_cvt_pk_bf16_f32 v234, v234, v235
	v_pk_fma_f32 v[236:237], v[238:239], v[252:253], v[236:237]
	v_lshlrev_b32_e32 v238, 16, v100
	v_cvt_pk_bf16_f32 v235, v236, v237
	v_lshlrev_b32_e32 v236, 16, v96
	v_and_b32_e32 v237, 0xffff0000, v96
	v_and_b32_e32 v239, 0xffff0000, v100
	v_pk_add_f32 v[238:239], v[238:239], v[236:237] neg_lo:[0,1] neg_hi:[0,1]
	v_and_b32_e32 v241, 0xffff0000, v101
	v_pk_fma_f32 v[236:237], v[238:239], v[246:247], v[236:237]
	v_lshlrev_b32_e32 v238, 16, v97
	v_and_b32_e32 v239, 0xffff0000, v97
	v_pk_add_f32 v[240:241], v[240:241], v[238:239] neg_lo:[0,1] neg_hi:[0,1]
	v_cvt_pk_bf16_f32 v236, v236, v237
	v_pk_fma_f32 v[238:239], v[240:241], v[248:249], v[238:239]
	s_nop 0
	v_cvt_pk_bf16_f32 v237, v238, v239
	ds_write_b128 v213, v[234:237] offset:46080
	ds_write_b128 v213, v[90:93] offset:64512
	v_lshlrev_b32_e32 v234, 16, v102
	v_and_b32_e32 v235, 0xffff0000, v102
	v_lshlrev_b32_e32 v236, 16, v106
	v_and_b32_e32 v237, 0xffff0000, v106
	v_pk_add_f32 v[236:237], v[236:237], v[234:235] neg_lo:[0,1] neg_hi:[0,1]
	s_nop 0
	v_pk_fma_f32 v[166:167], v[236:237], v[250:251], v[234:235]
	v_lshlrev_b32_e32 v234, 16, v103
	v_and_b32_e32 v235, 0xffff0000, v103
	v_lshlrev_b32_e32 v236, 16, v107
	v_and_b32_e32 v237, 0xffff0000, v107
	v_pk_add_f32 v[236:237], v[236:237], v[234:235] neg_lo:[0,1] neg_hi:[0,1]
	v_cvt_pk_bf16_f32 v166, v166, v167
	v_pk_fma_f32 v[168:169], v[236:237], v[252:253], v[234:235]
	v_lshlrev_b32_e32 v234, 16, v108
	v_cvt_pk_bf16_f32 v167, v168, v169
	v_lshlrev_b32_e32 v168, 16, v104
	v_and_b32_e32 v169, 0xffff0000, v104
	v_and_b32_e32 v235, 0xffff0000, v108
	v_pk_add_f32 v[234:235], v[234:235], v[168:169] neg_lo:[0,1] neg_hi:[0,1]
	s_nop 0
	v_pk_fma_f32 v[162:163], v[234:235], v[246:247], v[168:169]
	v_lshlrev_b32_e32 v234, 16, v109
	v_cvt_pk_bf16_f32 v168, v162, v163
	v_lshlrev_b32_e32 v162, 16, v105
	v_and_b32_e32 v163, 0xffff0000, v105
	v_and_b32_e32 v235, 0xffff0000, v109
	v_pk_add_f32 v[234:235], v[234:235], v[162:163] neg_lo:[0,1] neg_hi:[0,1]
	s_nop 0
	v_pk_fma_f32 v[162:163], v[234:235], v[248:249], v[162:163]
	s_nop 0
	v_cvt_pk_bf16_f32 v169, v162, v163
	ds_write_b128 v213, v[166:169] offset:50688
	ds_write_b128 v214, v[110:113] offset:13824
	s_cbranch_scc1 .LBB0_683
	global_load_dwordx4 v[246:249], v[194:195], off offset:256
	global_load_dwordx4 v[250:253], v[194:195], off offset:240
	v_lshl_add_u64 v[66:67], v[200:201], 0, v[180:181]
	v_add_co_u32_e32 v66, vcc, 0xa380000, v66
	v_lshl_add_u64 v[78:79], v[208:209], 0, v[180:181]
	s_nop 0
	v_addc_co_u32_e32 v67, vcc, 0, v67, vcc
	v_add_co_u32_e32 v78, vcc, 0xa380000, v78
	v_lshl_add_u64 v[70:71], v[186:187], 0, v[180:181]
	v_lshl_add_u64 v[74:75], v[210:211], 0, v[180:181]
	v_addc_co_u32_e32 v79, vcc, 0, v79, vcc
	v_lshl_add_u64 v[82:83], v[188:189], 0, v[180:181]
	global_load_dwordx4 v[66:69], v[66:67], off offset:384
	v_mov_b32_e32 v92, 0
	global_load_dwordx4 v[70:73], v[70:71], off offset:384
	v_mov_b32_e32 v93, v172
	global_load_dwordx4 v[74:77], v[74:75], off offset:-128
	v_mov_b64_e32 v[88:89], v[92:93]
	global_load_dwordx4 v[78:81], v[78:79], off offset:384
	v_mov_b64_e32 v[86:87], v[92:93]
	global_load_dwordx4 v[82:85], v[82:83], off offset:384
	s_and_saveexec_b64 s[2:3], s[0:1]
	s_cbranch_execz .LBB0_678
	v_lshl_add_u64 v[86:87], v[206:207], 0, v[180:181]
	global_load_dwordx4 v[86:89], v[86:87], off offset:-128

.LBB0_683:
	ds_read_b128 v[162:165], v233 offset:18432
	ds_read_b128 v[166:169], v232
	ds_read_b128 v[234:237], v233 offset:23040
	s_cmp_gt_u32 s14, 13
	s_cselect_b64 s[2:3], -1, 0
	s_and_b64 vcc, exec, s[2:3]
	s_waitcnt lgkmcnt(1)
	v_mfma_f32_32x32x16_bf16 v[50:65], v[162:165], v[166:169], v[50:65]
	s_waitcnt lgkmcnt(0)
	v_mfma_f32_32x32x16_bf16 v[34:49], v[234:237], v[166:169], v[34:49]
	ds_read_b128 v[166:169], v232 offset:4608
	s_waitcnt lgkmcnt(0)
	v_mfma_f32_32x32x16_bf16 v[18:33], v[162:165], v[166:169], v[18:33]
	v_mfma_f32_32x32x16_bf16 v[2:17], v[234:237], v[166:169], v[2:17]
	ds_read_b128 v[162:165], v233 offset:18464
	ds_read_b128 v[166:169], v232 offset:32
	ds_read_b128 v[234:237], v233 offset:23072
	s_waitcnt lgkmcnt(1)
	v_mfma_f32_32x32x16_bf16 v[50:65], v[162:165], v[166:169], v[50:65]
	s_waitcnt lgkmcnt(0)
	v_mfma_f32_32x32x16_bf16 v[34:49], v[234:237], v[166:169], v[34:49]
	ds_read_b128 v[166:169], v232 offset:4640
	s_waitcnt lgkmcnt(0)
	v_mfma_f32_32x32x16_bf16 v[18:33], v[162:165], v[166:169], v[18:33]
	v_mfma_f32_32x32x16_bf16 v[2:17], v[234:237], v[166:169], v[2:17]
	ds_read_b128 v[162:165], v233 offset:18496
	ds_read_b128 v[166:169], v232 offset:64
	ds_read_b128 v[234:237], v233 offset:23104
	s_waitcnt lgkmcnt(1)
	v_mfma_f32_32x32x16_bf16 v[50:65], v[162:165], v[166:169], v[50:65]
	s_waitcnt lgkmcnt(0)
	v_mfma_f32_32x32x16_bf16 v[34:49], v[234:237], v[166:169], v[34:49]
	ds_read_b128 v[166:169], v232 offset:4672
	s_waitcnt lgkmcnt(0)
	v_mfma_f32_32x32x16_bf16 v[18:33], v[162:165], v[166:169], v[18:33]
	v_mfma_f32_32x32x16_bf16 v[2:17], v[234:237], v[166:169], v[2:17]
	ds_read_b128 v[162:165], v233 offset:18528
	ds_read_b128 v[166:169], v232 offset:96
	ds_read_b128 v[234:237], v233 offset:23136
	s_waitcnt lgkmcnt(1)
	v_mfma_f32_32x32x16_bf16 v[50:65], v[162:165], v[166:169], v[50:65]
	s_waitcnt lgkmcnt(0)
	v_mfma_f32_32x32x16_bf16 v[34:49], v[234:237], v[166:169], v[34:49]
	ds_read_b128 v[166:169], v232 offset:4704
	s_waitcnt lgkmcnt(0)
	s_barrier
	v_mfma_f32_32x32x16_bf16 v[18:33], v[162:165], v[166:169], v[18:33]
	v_mfma_f32_32x32x16_bf16 v[2:17], v[234:237], v[166:169], v[2:17]
	s_cbranch_vccnz .LBB0_674
	s_waitcnt vmcnt(8)
	v_lshlrev_b32_e32 v234, 16, v114
	v_and_b32_e32 v235, 0xffff0000, v114
	v_lshlrev_b32_e32 v236, 16, v118
	v_and_b32_e32 v237, 0xffff0000, v118
	v_pk_add_f32 v[236:237], v[236:237], v[234:235] neg_lo:[0,1] neg_hi:[0,1]
	v_lshlrev_b32_e32 v238, 16, v119
	v_and_b32_e32 v239, 0xffff0000, v119
	v_lshlrev_b32_e32 v240, 16, v121
	v_and_b32_e32 v241, 0xffff0000, v121
	s_cmp_gt_u32 s14, 11
	v_pk_fma_f32 v[234:235], v[236:237], v[250:251], v[234:235]
	v_lshlrev_b32_e32 v236, 16, v115
	v_and_b32_e32 v237, 0xffff0000, v115
	v_pk_add_f32 v[238:239], v[238:239], v[236:237] neg_lo:[0,1] neg_hi:[0,1]
	v_cvt_pk_bf16_f32 v234, v234, v235
	v_pk_fma_f32 v[236:237], v[238:239], v[252:253], v[236:237]
	v_lshlrev_b32_e32 v238, 16, v120
	v_cvt_pk_bf16_f32 v235, v236, v237
	v_lshlrev_b32_e32 v236, 16, v116
	v_and_b32_e32 v237, 0xffff0000, v116
	v_and_b32_e32 v239, 0xffff0000, v120
	v_pk_add_f32 v[238:239], v[238:239], v[236:237] neg_lo:[0,1] neg_hi:[0,1]
	s_nop 0
	v_pk_fma_f32 v[236:237], v[238:239], v[246:247], v[236:237]
	v_lshlrev_b32_e32 v238, 16, v117
	v_and_b32_e32 v239, 0xffff0000, v117
	v_pk_add_f32 v[240:241], v[240:241], v[238:239] neg_lo:[0,1] neg_hi:[0,1]
	v_cvt_pk_bf16_f32 v236, v236, v237
	v_pk_fma_f32 v[238:239], v[240:241], v[248:249], v[238:239]
	v_lshlrev_b32_e32 v240, 16, v133
	v_cvt_pk_bf16_f32 v237, v238, v239
	ds_write_b128 v213, v[234:237]
	ds_write_b128 v213, v[122:125] offset:18432
	v_lshlrev_b32_e32 v234, 16, v126
	v_and_b32_e32 v235, 0xffff0000, v126
	v_lshlrev_b32_e32 v236, 16, v130
	v_and_b32_e32 v237, 0xffff0000, v130
	v_pk_add_f32 v[236:237], v[236:237], v[234:235] neg_lo:[0,1] neg_hi:[0,1]
	v_lshlrev_b32_e32 v238, 16, v131
	v_pk_fma_f32 v[234:235], v[236:237], v[250:251], v[234:235]
	v_lshlrev_b32_e32 v236, 16, v127
	v_and_b32_e32 v237, 0xffff0000, v127
	v_and_b32_e32 v239, 0xffff0000, v131
	v_pk_add_f32 v[238:239], v[238:239], v[236:237] neg_lo:[0,1] neg_hi:[0,1]
	v_cvt_pk_bf16_f32 v234, v234, v235
	v_pk_fma_f32 v[236:237], v[238:239], v[252:253], v[236:237]
	v_lshlrev_b32_e32 v238, 16, v132
	v_cvt_pk_bf16_f32 v235, v236, v237
	v_lshlrev_b32_e32 v236, 16, v128
	v_and_b32_e32 v237, 0xffff0000, v128
	v_and_b32_e32 v239, 0xffff0000, v132
	v_pk_add_f32 v[238:239], v[238:239], v[236:237] neg_lo:[0,1] neg_hi:[0,1]
	v_and_b32_e32 v241, 0xffff0000, v133
	v_pk_fma_f32 v[236:237], v[238:239], v[246:247], v[236:237]
	v_lshlrev_b32_e32 v238, 16, v129
	v_and_b32_e32 v239, 0xffff0000, v129
	v_pk_add_f32 v[240:241], v[240:241], v[238:239] neg_lo:[0,1] neg_hi:[0,1]
	v_cvt_pk_bf16_f32 v236, v236, v237
	v_pk_fma_f32 v[238:239], v[240:241], v[248:249], v[238:239]
	v_lshlrev_b32_e32 v240, 16, v149
	v_cvt_pk_bf16_f32 v237, v238, v239
	ds_write_b128 v213, v[234:237] offset:4608
	ds_write_b128 v213, v[134:137] offset:23040
	v_lshlrev_b32_e32 v234, 16, v142
	v_and_b32_e32 v235, 0xffff0000, v142
	v_lshlrev_b32_e32 v236, 16, v146
	v_and_b32_e32 v237, 0xffff0000, v146
	v_pk_add_f32 v[236:237], v[236:237], v[234:235] neg_lo:[0,1] neg_hi:[0,1]
	v_lshlrev_b32_e32 v238, 16, v147
	v_pk_fma_f32 v[234:235], v[236:237], v[250:251], v[234:235]
	v_lshlrev_b32_e32 v236, 16, v143
	v_and_b32_e32 v237, 0xffff0000, v143
	v_and_b32_e32 v239, 0xffff0000, v147
	v_pk_add_f32 v[238:239], v[238:239], v[236:237] neg_lo:[0,1] neg_hi:[0,1]
	v_cvt_pk_bf16_f32 v234, v234, v235
	v_pk_fma_f32 v[236:237], v[238:239], v[252:253], v[236:237]
	v_lshlrev_b32_e32 v238, 16, v148
	v_cvt_pk_bf16_f32 v235, v236, v237
	v_lshlrev_b32_e32 v236, 16, v144
	v_and_b32_e32 v237, 0xffff0000, v144
	v_and_b32_e32 v239, 0xffff0000, v148
	v_pk_add_f32 v[238:239], v[238:239], v[236:237] neg_lo:[0,1] neg_hi:[0,1]
	v_and_b32_e32 v241, 0xffff0000, v149
	v_pk_fma_f32 v[236:237], v[238:239], v[246:247], v[236:237]
	v_lshlrev_b32_e32 v238, 16, v145
	v_and_b32_e32 v239, 0xffff0000, v145
	v_pk_add_f32 v[240:241], v[240:241], v[238:239] neg_lo:[0,1] neg_hi:[0,1]
	v_cvt_pk_bf16_f32 v236, v236, v237
	v_pk_fma_f32 v[238:239], v[240:241], v[248:249], v[238:239]
	s_nop 0
	v_cvt_pk_bf16_f32 v237, v238, v239
	ds_write_b128 v213, v[234:237] offset:9216
	ds_write_b128 v213, v[138:141] offset:27648
	v_lshlrev_b32_e32 v234, 16, v150
	v_and_b32_e32 v235, 0xffff0000, v150
	v_lshlrev_b32_e32 v236, 16, v154
	v_and_b32_e32 v237, 0xffff0000, v154
	v_pk_add_f32 v[236:237], v[236:237], v[234:235] neg_lo:[0,1] neg_hi:[0,1]
	s_nop 0
	v_pk_fma_f32 v[166:167], v[236:237], v[250:251], v[234:235]
	v_lshlrev_b32_e32 v234, 16, v151
	v_and_b32_e32 v235, 0xffff0000, v151
	v_lshlrev_b32_e32 v236, 16, v155
	v_and_b32_e32 v237, 0xffff0000, v155
	v_pk_add_f32 v[236:237], v[236:237], v[234:235] neg_lo:[0,1] neg_hi:[0,1]
	v_cvt_pk_bf16_f32 v166, v166, v167
	v_pk_fma_f32 v[168:169], v[236:237], v[252:253], v[234:235]
	v_lshlrev_b32_e32 v234, 16, v156
	v_cvt_pk_bf16_f32 v167, v168, v169
	v_lshlrev_b32_e32 v168, 16, v152
	v_and_b32_e32 v169, 0xffff0000, v152
	v_and_b32_e32 v235, 0xffff0000, v156
	v_pk_add_f32 v[234:235], v[234:235], v[168:169] neg_lo:[0,1] neg_hi:[0,1]
	s_nop 0
	v_pk_fma_f32 v[162:163], v[234:235], v[246:247], v[168:169]
	v_lshlrev_b32_e32 v234, 16, v157
	v_cvt_pk_bf16_f32 v168, v162, v163
	v_lshlrev_b32_e32 v162, 16, v153
	v_and_b32_e32 v163, 0xffff0000, v153
	v_and_b32_e32 v235, 0xffff0000, v157
	v_pk_add_f32 v[234:235], v[234:235], v[162:163] neg_lo:[0,1] neg_hi:[0,1]
	s_nop 0
	v_pk_fma_f32 v[162:163], v[234:235], v[248:249], v[162:163]
	s_nop 0
	v_cvt_pk_bf16_f32 v169, v162, v163
	ds_write_b128 v213, v[166:169] offset:13824
	ds_write_b128 v213, v[158:161] offset:32256
	global_load_dwordx4 v[246:249], v[194:195], off offset:512
	global_load_dwordx4 v[250:253], v[194:195], off offset:496
	s_cbranch_scc1 .Lmixpf_b_last
	v_lshl_add_u64 v[114:115], v[200:201], 0, v[180:181]
	v_add_co_u32_e32 v114, vcc, 0xa380000, v114
	v_lshl_add_u64 v[126:127], v[208:209], 0, v[180:181]
	s_nop 0
	v_addc_co_u32_e32 v115, vcc, 0, v115, vcc
	v_add_co_u32_e32 v126, vcc, 0xa380000, v126
	v_lshl_add_u64 v[118:119], v[186:187], 0, v[180:181]
	v_lshl_add_u64 v[122:123], v[210:211], 0, v[180:181]
	v_addc_co_u32_e32 v127, vcc, 0, v127, vcc
	v_lshl_add_u64 v[130:131], v[188:189], 0, v[180:181]
	global_load_dwordx4 v[114:117], v[114:115], off offset:512
	v_mov_b32_e32 v140, 0
	global_load_dwordx4 v[118:121], v[118:119], off offset:512
	v_mov_b32_e32 v141, v172
	global_load_dwordx4 v[122:125], v[122:123], off
	v_mov_b64_e32 v[136:137], v[140:141]
	global_load_dwordx4 v[126:129], v[126:127], off offset:512
	v_mov_b64_e32 v[134:135], v[140:141]
	global_load_dwordx4 v[130:133], v[130:131], off offset:512
	s_and_saveexec_b64 s[22:23], s[0:1]
	s_cbranch_execz .LBB0_687
	v_lshl_add_u64 v[134:135], v[206:207], 0, v[180:181]
	global_load_dwordx4 v[134:137], v[134:135], off
